# static GEMM priority raise moved to waves 0..3 instead of 4..7
# speedup vs baseline: 1.0099x; 1.0044x over previous
.LBB0_86:
	s_or_b64 exec, exec, s[0:1]
	s_setprio 0
	v_readfirstlane_b32 s0, v180
	s_nop 1
	s_cmpk_lt_u32 s0, 0x100
	s_cbranch_scc0 .Lprio_86
	s_setprio 1
